# nt hint on the read-once row loads of the f32-input norm phase (x) and the final norm (XF) (on v67)
# speedup vs baseline: 1.0188x; 1.0188x over previous
; __device__ __forceinline__ void norm_mod_phase(const Ctx& F, const float* xin, const float* gain, const float* shift, const float* scale) {
;     ...
;             for (int u = 0; u < 4; ++u) { const float* xr = xin + (size_t)(row0 + r + u) * D; s[u] = 0.f;
; #pragma unroll
;                 for (int j = 0; j < 4; ++j) v[u][j] = *(const f32x4*)(xr + 4 * ln + 256 * j); }
; #pragma unroll
;             for (int u = 0; u < 4; ++u) {
; #pragma unroll
;                 for (int j = 0; j < 4; ++j) s[u] += (v[u][j][0] * v[u][j][0] + v[u][j][1] * v[u][j][1]) + (v[u][j][2] * v[u][j][2] + v[u][j][3] * v[u][j][3]);
.LBB0_164:
	v_lshl_add_u64 v[28:29], s[36:37], 0, v[80:81]
	v_lshl_add_u64 v[30:31], s[40:41], 0, v[80:81]
	v_lshl_add_u64 v[106:107], s[54:55], 0, v[80:81]
	v_lshl_add_u64 v[110:111], s[30:31], 0, v[80:81]
	flat_load_dwordx4 v[76:79], v[28:29] nt
	flat_load_dwordx4 v[68:71], v[28:29] offset:1024 nt
	flat_load_dwordx4 v[64:67], v[28:29] offset:3072 nt
	flat_load_dwordx4 v[72:75], v[28:29] offset:2048 nt
	flat_load_dwordx4 v[60:63], v[30:31] nt
	flat_load_dwordx4 v[56:59], v[30:31] offset:1024 nt
	flat_load_dwordx4 v[52:55], v[30:31] offset:2048 nt
	flat_load_dwordx4 v[48:51], v[30:31] offset:3072 nt
	flat_load_dwordx4 v[44:47], v[106:107] nt
	flat_load_dwordx4 v[40:43], v[106:107] offset:1024 nt
	flat_load_dwordx4 v[36:39], v[106:107] offset:2048 nt
	flat_load_dwordx4 v[32:35], v[106:107] offset:3072 nt
	flat_load_dwordx4 v[24:27], v[110:111] nt
	flat_load_dwordx4 v[20:23], v[110:111] offset:1024 nt
	flat_load_dwordx4 v[16:19], v[110:111] offset:2048 nt
	flat_load_dwordx4 v[28:31], v[110:111] offset:3072 nt
	v_lshl_add_u64 v[108:109], s[28:29], 0, v[88:89]
	v_add_co_u32_e32 v112, vcc, s42, v108
	v_lshl_add_u64 v[118:119], s[38:39], 0, v[88:89]
	s_nop 0
	v_addc_co_u32_e32 v113, vcc, 0, v109, vcc
	v_add_co_u32_e32 v110, vcc, s42, v118
	v_lshl_add_u64 v[120:121], s[52:53], 0, v[88:89]
	s_nop 0
	v_addc_co_u32_e32 v111, vcc, 0, v119, vcc
	v_add_co_u32_e32 v108, vcc, s42, v120
	v_lshl_add_u64 v[122:123], s[34:35], 0, v[88:89]
	s_nop 0
	v_addc_co_u32_e32 v109, vcc, 0, v121, vcc
	v_add_co_u32_e32 v106, vcc, s42, v122
	s_add_u32 s28, s28, 0x2000
	s_nop 0
	v_addc_co_u32_e32 v107, vcc, 0, v123, vcc
	s_addc_u32 s29, s29, 0
	s_add_i32 s21, s21, 4
	s_add_u32 s30, s30, 0x4000
	s_addc_u32 s31, s31, 0
	s_add_u32 s34, s34, 0x2000
	s_addc_u32 s35, s35, 0
	s_add_u32 s36, s36, 0x4000
	s_addc_u32 s37, s37, 0
	s_add_u32 s38, s38, 0x2000
	s_addc_u32 s39, s39, 0
	s_add_u32 s40, s40, 0x4000
	s_addc_u32 s41, s41, 0
	s_add_u32 s52, s52, 0x2000
	s_addc_u32 s53, s53, 0
	s_add_u32 s54, s54, 0x4000
	s_addc_u32 s55, s55, 0
	s_cmp_gt_u32 s21, 27
	s_waitcnt vmcnt(0) lgkmcnt(0)
	v_pk_mul_f32 v[118:119], v[78:79], v[78:79]
	v_pk_mul_f32 v[120:121], v[76:77], v[76:77]
	v_pk_mul_f32 v[122:123], v[70:71], v[70:71]
	v_pk_mul_f32 v[124:125], v[68:69], v[68:69]
	v_mul_f32_e32 v126, v73, v73
	v_mul_f32_e32 v128, v75, v75
	v_pk_mul_f32 v[130:131], v[62:63], v[62:63]
	v_pk_mul_f32 v[132:133], v[60:61], v[60:61]
	v_pk_mul_f32 v[134:135], v[58:59], v[58:59]
	v_pk_mul_f32 v[136:137], v[56:57], v[56:57]
	v_mul_f32_e32 v138, v53, v53
	v_mul_f32_e32 v140, v55, v55
	v_pk_mul_f32 v[142:143], v[46:47], v[46:47]
	v_pk_mul_f32 v[144:145], v[44:45], v[44:45]
	v_pk_mul_f32 v[146:147], v[42:43], v[42:43]
	v_pk_mul_f32 v[148:149], v[40:41], v[40:41]
	v_pk_mov_b32 v[166:167], v[120:121], v[118:119] op_sel:[1,0]
	v_mov_b32_e32 v121, v119
	v_pk_mov_b32 v[118:119], v[124:125], v[122:123] op_sel:[1,0]
	v_mov_b32_e32 v125, v123
	v_mul_f32_e32 v150, v37, v37
	v_mul_f32_e32 v152, v39, v39
	v_pk_mul_f32 v[154:155], v[26:27], v[26:27]
	v_pk_mul_f32 v[156:157], v[24:25], v[24:25]
	v_pk_mul_f32 v[158:159], v[22:23], v[22:23]
	v_pk_mul_f32 v[160:161], v[20:21], v[20:21]
	v_pk_fma_f32 v[122:123], v[72:73], v[72:73], v[126:127] op_sel_hi:[1,1,0]
	v_pk_fma_f32 v[126:127], v[74:75], v[74:75], v[128:129] op_sel_hi:[1,1,0]
	v_pk_mov_b32 v[128:129], v[132:133], v[130:131] op_sel:[1,0]
	v_mov_b32_e32 v133, v131
	v_pk_mov_b32 v[130:131], v[136:137], v[134:135] op_sel:[1,0]
	v_mov_b32_e32 v137, v135
	v_pk_fma_f32 v[134:135], v[52:53], v[52:53], v[138:139] op_sel_hi:[1,1,0]
	v_pk_fma_f32 v[138:139], v[54:55], v[54:55], v[140:141] op_sel_hi:[1,1,0]
	v_pk_mov_b32 v[140:141], v[144:145], v[142:143] op_sel:[1,0]
	v_mov_b32_e32 v145, v143
	v_pk_mov_b32 v[142:143], v[148:149], v[146:147] op_sel:[1,0]
	v_mov_b32_e32 v149, v147
	v_pk_add_f32 v[120:121], v[166:167], v[120:121]
	v_pk_add_f32 v[118:119], v[118:119], v[124:125]
	v_mul_f32_e32 v117, v66, v66
	v_mul_f32_e32 v165, v67, v67
	v_mul_f32_e32 v168, v64, v64
	v_mul_f32_e32 v169, v65, v65
	v_pk_fma_f32 v[146:147], v[36:37], v[36:37], v[150:151] op_sel_hi:[1,1,0]
	v_pk_fma_f32 v[150:151], v[38:39], v[38:39], v[152:153] op_sel_hi:[1,1,0]
	v_pk_mov_b32 v[152:153], v[156:157], v[154:155] op_sel:[1,0]
	v_mov_b32_e32 v157, v155
	v_pk_mov_b32 v[154:155], v[160:161], v[158:159] op_sel:[1,0]
	v_mov_b32_e32 v161, v159
	v_pk_add_f32 v[124:125], v[128:129], v[132:133]
	v_pk_add_f32 v[128:129], v[130:131], v[136:137]
	v_pk_add_f32 v[130:131], v[140:141], v[144:145]
	v_pk_add_f32 v[132:133], v[142:143], v[148:149]
	v_pk_add_f32 v[120:121], v[120:121], v[120:121] op_sel:[0,1] op_sel_hi:[1,0]
	v_pk_add_f32 v[118:119], v[118:119], v[118:119] op_sel:[0,1] op_sel_hi:[1,0]
	v_mul_f32_e32 v170, v50, v50
	v_mul_f32_e32 v171, v51, v51
	v_mul_f32_e32 v172, v48, v48
	v_mul_f32_e32 v173, v49, v49
	v_mul_f32_e32 v174, v34, v34
	v_mul_f32_e32 v175, v35, v35
	v_mul_f32_e32 v176, v32, v32
	v_mul_f32_e32 v177, v33, v33
	v_mul_f32_e32 v162, v17, v17
	v_mul_f32_e32 v164, v19, v19
	v_mov_b32_e32 v123, v117
	v_mov_b32_e32 v127, v165
	v_pk_add_f32 v[136:137], v[152:153], v[156:157]
	v_pk_add_f32 v[140:141], v[154:155], v[160:161]
	v_pk_add_f32 v[124:125], v[124:125], v[124:125] op_sel:[0,1] op_sel_hi:[1,0]
	v_pk_add_f32 v[128:129], v[128:129], v[128:129] op_sel:[0,1] op_sel_hi:[1,0]
	v_pk_add_f32 v[130:131], v[130:131], v[130:131] op_sel:[0,1] op_sel_hi:[1,0]
	v_pk_add_f32 v[132:133], v[132:133], v[132:133] op_sel:[0,1] op_sel_hi:[1,0]
	v_mov_b32_e32 v121, v168
	v_mov_b32_e32 v119, v169
	v_mul_f32_e32 v178, v30, v30
	v_mul_f32_e32 v179, v31, v31
	v_mul_f32_e32 v180, v28, v28
	v_mul_f32_e32 v181, v29, v29
; __device__ __forceinline__ float wave_sum_fast(float x) { x = reduce16(x); return (rl_(x, 0) + rl_(x, 16)) + (rl_(x, 32) + rl_(x, 48)); }
; __device__ __forceinline__ void norm_mod_phase(const Ctx& F, const float* xin, const float* gain, const float* shift, const float* scale) {
;     ...
;                 for (int j = 0; j < 4; ++j) s[u] += (v[u][j][0] * v[u][j][0] + v[u][j][1] * v[u][j][1]) + (v[u][j][2] * v[u][j][2] + v[u][j][3] * v[u][j][3]);
;                 s[u] = wave_sum_fast(s[u]); }
; #pragma unroll
;             for (int u = 0; u < 4; ++u) { const float rstd = 1.0f / sqrtf(s[u] * (1.0f / D) + 1e-6f);
	v_pk_fma_f32 v[158:159], v[16:17], v[16:17], v[162:163] op_sel_hi:[1,1,0]
	v_pk_fma_f32 v[162:163], v[18:19], v[18:19], v[164:165] op_sel_hi:[1,1,0]
	v_mov_b32_e32 v135, v170
	v_mov_b32_e32 v139, v171
	v_mov_b32_e32 v147, v174
	v_mov_b32_e32 v151, v175
	v_pk_add_f32 v[122:123], v[122:123], v[126:127]
	v_pk_add_f32 v[136:137], v[136:137], v[136:137] op_sel:[0,1] op_sel_hi:[1,0]
	v_pk_add_f32 v[140:141], v[140:141], v[140:141] op_sel:[0,1] op_sel_hi:[1,0]
	v_mov_b32_e32 v125, v172
	v_mov_b32_e32 v129, v173
	v_mov_b32_e32 v131, v176
	v_mov_b32_e32 v133, v177
	v_pk_add_f32 v[118:119], v[120:121], v[118:119]
	v_mov_b32_e32 v159, v178
	v_mov_b32_e32 v163, v179
	v_pk_add_f32 v[126:127], v[134:135], v[138:139]
	v_pk_add_f32 v[134:135], v[146:147], v[150:151]
	v_mov_b32_e32 v137, v180
	v_mov_b32_e32 v141, v181
	v_pk_add_f32 v[120:121], v[124:125], v[128:129]
	v_pk_add_f32 v[124:125], v[130:131], v[132:133]
	v_pk_add_f32 v[118:119], v[118:119], v[122:123]
	v_pk_add_f32 v[138:139], v[158:159], v[162:163]
	v_pk_add_f32 v[128:129], v[136:137], v[140:141]
	v_pk_add_f32 v[120:121], v[120:121], v[126:127]
	v_pk_add_f32 v[122:123], v[124:125], v[134:135]
	v_add_f32_e32 v117, v118, v119
	v_pk_add_f32 v[124:125], v[128:129], v[138:139]
	v_add_f32_e32 v118, v120, v121
	v_add_f32_e32 v119, v122, v123
	v_add_f32_dpp v117, v117, v117 quad_perm:[1,0,3,2] row_mask:0xf bank_mask:0xf bound_ctrl:1
	v_add_f32_e32 v120, v124, v125
	v_add_f32_dpp v118, v118, v118 quad_perm:[1,0,3,2] row_mask:0xf bank_mask:0xf bound_ctrl:1
	v_add_f32_dpp v119, v119, v119 quad_perm:[1,0,3,2] row_mask:0xf bank_mask:0xf bound_ctrl:1
	v_add_f32_dpp v117, v117, v117 quad_perm:[2,3,0,1] row_mask:0xf bank_mask:0xf bound_ctrl:1
	v_add_f32_dpp v120, v120, v120 quad_perm:[1,0,3,2] row_mask:0xf bank_mask:0xf bound_ctrl:1
	v_add_f32_dpp v118, v118, v118 quad_perm:[2,3,0,1] row_mask:0xf bank_mask:0xf bound_ctrl:1
	v_add_f32_dpp v119, v119, v119 quad_perm:[2,3,0,1] row_mask:0xf bank_mask:0xf bound_ctrl:1
	v_add_f32_dpp v117, v117, v117 row_half_mirror row_mask:0xf bank_mask:0xf bound_ctrl:1
	v_add_f32_dpp v120, v120, v120 quad_perm:[2,3,0,1] row_mask:0xf bank_mask:0xf bound_ctrl:1
	v_add_f32_dpp v118, v118, v118 row_half_mirror row_mask:0xf bank_mask:0xf bound_ctrl:1
	v_add_f32_dpp v119, v119, v119 row_half_mirror row_mask:0xf bank_mask:0xf bound_ctrl:1
	v_add_f32_dpp v117, v117, v117 row_mirror row_mask:0xf bank_mask:0xf bound_ctrl:1
	v_add_f32_dpp v120, v120, v120 row_half_mirror row_mask:0xf bank_mask:0xf bound_ctrl:1
	v_add_f32_dpp v118, v118, v118 row_mirror row_mask:0xf bank_mask:0xf bound_ctrl:1
	v_add_f32_dpp v119, v119, v119 row_mirror row_mask:0xf bank_mask:0xf bound_ctrl:1
	v_readlane_b32 s12, v117, 16
	v_readlane_b32 s13, v117, 48
	v_add_f32_dpp v120, v120, v120 row_mirror row_mask:0xf bank_mask:0xf bound_ctrl:1
	v_readlane_b32 s4, v117, 0
	v_readlane_b32 s5, v117, 32
	v_readlane_b32 s6, v118, 0
	v_readlane_b32 s14, v118, 16
	v_readlane_b32 s7, v118, 32
	v_readlane_b32 s15, v118, 48
	v_readlane_b32 s8, v119, 0
	v_readlane_b32 s16, v119, 16
	v_readlane_b32 s9, v119, 32
	v_readlane_b32 s17, v119, 48
	v_mov_b32_e32 v118, s12
	v_mov_b32_e32 v119, s13
	v_readlane_b32 s10, v120, 0
	v_readlane_b32 s23, v120, 16
	v_readlane_b32 s11, v120, 32
	v_readlane_b32 s25, v120, 48
	v_mov_b32_e32 v120, s14
	v_mov_b32_e32 v121, s15
	v_mov_b32_e32 v122, s16
	v_mov_b32_e32 v123, s17
	v_pk_add_f32 v[118:119], s[4:5], v[118:119]
	v_pk_add_f32 v[120:121], s[6:7], v[120:121]
	v_pk_add_f32 v[122:123], s[8:9], v[122:123]
	v_add_f32_e32 v117, v118, v119
	v_mov_b32_e32 v124, s23
	v_mov_b32_e32 v125, s25
	v_add_f32_e32 v118, v120, v121
	v_add_f32_e32 v119, v122, v123
	v_fmamk_f32 v117, v117, 0x3a800000, v115
	v_pk_add_f32 v[124:125], s[10:11], v[124:125]
	v_fmamk_f32 v118, v118, 0x3a800000, v115
	v_fmamk_f32 v119, v119, 0x3a800000, v115
	v_mul_f32_e32 v121, 0x4f800000, v117
	v_cmp_gt_f32_e64 s[8:9], s33, v117
	v_add_f32_e32 v120, v124, v125
	v_mul_f32_e32 v122, 0x4f800000, v118
	v_cmp_gt_f32_e32 vcc, s33, v118
	v_mul_f32_e32 v123, 0x4f800000, v119
	v_cmp_gt_f32_e64 s[4:5], s33, v119
	v_cndmask_b32_e64 v117, v117, v121, s[8:9]
	v_fmamk_f32 v120, v120, 0x3a800000, v115
	v_cndmask_b32_e32 v118, v118, v122, vcc
	v_cndmask_b32_e64 v119, v119, v123, s[4:5]
	v_sqrt_f32_e32 v121, v117
	v_mul_f32_e32 v124, 0x4f800000, v120
	v_cmp_gt_f32_e64 s[6:7], s33, v120
	v_sqrt_f32_e32 v122, v118
	v_sqrt_f32_e32 v123, v119
	v_cndmask_b32_e64 v120, v120, v124, s[6:7]
	v_sqrt_f32_e32 v124, v120
	v_add_u32_e32 v125, -1, v121
	v_add_u32_e32 v126, 1, v121
	v_add_u32_e32 v127, -1, v122
	v_add_u32_e32 v129, -1, v123
	v_fma_f32 v133, -v125, v121, v117
	v_add_u32_e32 v128, 1, v122
	v_add_u32_e32 v130, 1, v123
	v_fma_f32 v134, -v126, v121, v117
	v_fma_f32 v135, -v127, v122, v118
	v_fma_f32 v137, -v129, v123, v119
	v_cmp_ge_f32_e64 s[10:11], 0, v133
	v_add_u32_e32 v131, -1, v124
	v_fma_f32 v136, -v128, v122, v118
	v_fma_f32 v138, -v130, v123, v119
	v_cndmask_b32_e64 v121, v121, v125, s[10:11]
	v_cmp_ge_f32_e64 s[10:11], 0, v135
	v_cmp_ge_f32_e64 s[12:13], 0, v137
	v_cmp_lt_f32_e64 s[16:17], 0, v134
	v_add_u32_e32 v132, 1, v124
	v_fma_f32 v139, -v131, v124, v120
	v_cndmask_b32_e64 v122, v122, v127, s[10:11]
	v_cmp_lt_f32_e64 s[10:11], 0, v136
	v_cndmask_b32_e64 v123, v123, v129, s[12:13]
	v_cmp_lt_f32_e64 s[12:13], 0, v138
	v_cndmask_b32_e64 v121, v121, v126, s[16:17]
	v_fma_f32 v140, -v132, v124, v120
	v_cmp_ge_f32_e64 s[14:15], 0, v139
	v_cndmask_b32_e64 v122, v122, v128, s[10:11]
	v_cndmask_b32_e64 v123, v123, v130, s[12:13]
	v_mul_f32_e32 v125, 0x37800000, v121
	v_cndmask_b32_e64 v124, v124, v131, s[14:15]
	v_cmp_lt_f32_e64 s[14:15], 0, v140
; __device__ __forceinline__ unsigned pk2(float lo, float hi) { f32x2 v = {lo, hi}; bf16x2_t b = __builtin_convertvector(v, bf16x2_t); return __builtin_bit_cast(unsigned, b); }
; __device__ __forceinline__ void norm_mod_phase(const Ctx& F, const float* xin, const float* gain, const float* shift, const float* scale) {
;     ...
;             for (int u = 0; u < 4; ++u) { const float rstd = 1.0f / sqrtf(s[u] * (1.0f / D) + 1e-6f);
; #pragma unroll
;                 for (int j = 0; j < 4; ++j) { const f32x4 o = v[u][j] * rstd * ga[j] + sh[j]; u32x2 w; w.x = pk2(o[0], o[1]); w.y = pk2(o[2], o[3]);
;                     *(u32x2*)(hb + (size_t)(row0 + r + u) * D + 4 * ln + 256 * j) = w; } }
	v_mul_f32_e32 v126, 0x37800000, v122
	v_mul_f32_e32 v127, 0x37800000, v123
	v_cndmask_b32_e64 v121, v121, v125, s[8:9]
	v_cmp_class_f32_e64 s[8:9], v117, v116
	v_cndmask_b32_e64 v124, v124, v132, s[14:15]
	v_cndmask_b32_e32 v122, v122, v126, vcc
	v_cmp_class_f32_e32 vcc, v118, v116
	v_cndmask_b32_e64 v123, v123, v127, s[4:5]
	v_cmp_class_f32_e64 s[4:5], v119, v116
	v_cndmask_b32_e64 v117, v121, v117, s[8:9]
	v_mul_f32_e32 v128, 0x37800000, v124
	v_cndmask_b32_e32 v121, v122, v118, vcc
	v_cndmask_b32_e64 v119, v123, v119, s[4:5]
	v_div_scale_f32 v118, s[4:5], v117, v117, 1.0
	v_cndmask_b32_e64 v124, v124, v128, s[6:7]
	v_cmp_class_f32_e64 s[6:7], v120, v116
	v_div_scale_f32 v123, s[4:5], v121, v121, 1.0
	v_rcp_f32_e32 v129, v118
	v_cndmask_b32_e64 v120, v124, v120, s[6:7]
	v_div_scale_f32 v125, s[6:7], v119, v119, 1.0
	v_rcp_f32_e32 v130, v123
	v_div_scale_f32 v127, s[8:9], v120, v120, 1.0
	v_rcp_f32_e32 v131, v125
	v_rcp_f32_e32 v132, v127
	v_fma_f32 v133, -v118, v129, 1.0
	v_div_scale_f32 v122, vcc, 1.0, v117, 1.0
	v_fma_f32 v134, -v123, v130, 1.0
	v_fmac_f32_e32 v129, v133, v129
	v_div_scale_f32 v124, s[4:5], 1.0, v121, 1.0
	v_fma_f32 v135, -v125, v131, 1.0
	v_fmac_f32_e32 v130, v134, v130
	v_mul_f32_e32 v133, v122, v129
	v_div_scale_f32 v126, s[6:7], 1.0, v119, 1.0
	v_fma_f32 v136, -v127, v132, 1.0
	v_fmac_f32_e32 v131, v135, v131
	v_mul_f32_e32 v134, v124, v130
	v_fma_f32 v137, -v118, v133, v122
	v_div_scale_f32 v128, s[8:9], 1.0, v120, 1.0
	v_fmac_f32_e32 v132, v136, v132
	v_mul_f32_e32 v135, v126, v131
	v_fma_f32 v138, -v123, v134, v124
	v_fmac_f32_e32 v133, v137, v129
	v_mul_f32_e32 v136, v128, v132
	v_fma_f32 v139, -v125, v135, v126
	v_fmac_f32_e32 v134, v138, v130
	v_fma_f32 v118, -v118, v133, v122
	v_fma_f32 v140, -v127, v136, v128
	v_fmac_f32_e32 v135, v139, v131
	v_fma_f32 v122, -v123, v134, v124
	v_div_fmas_f32 v118, v118, v129, v133
	s_mov_b64 vcc, s[4:5]
	v_fmac_f32_e32 v136, v140, v132
	v_fma_f32 v123, -v125, v135, v126
	v_div_fixup_f32 v118, v118, v117, 1.0
	v_div_fmas_f32 v117, v122, v130, v134
	s_mov_b64 vcc, s[6:7]
	v_fma_f32 v124, -v127, v136, v128
	v_pk_mul_f32 v[76:77], v[76:77], v[118:119] op_sel_hi:[1,0]
	v_pk_mul_f32 v[78:79], v[78:79], v[118:119] op_sel_hi:[1,0]
	v_pk_mul_f32 v[68:69], v[68:69], v[118:119] op_sel_hi:[1,0]
	v_pk_mul_f32 v[70:71], v[70:71], v[118:119] op_sel_hi:[1,0]
	v_pk_mul_f32 v[72:73], v[72:73], v[118:119] op_sel_hi:[1,0]
	v_pk_mul_f32 v[74:75], v[74:75], v[118:119] op_sel_hi:[1,0]
	v_pk_mul_f32 v[64:65], v[64:65], v[118:119] op_sel_hi:[1,0]
	v_pk_mul_f32 v[66:67], v[66:67], v[118:119] op_sel_hi:[1,0]
	v_div_fixup_f32 v118, v117, v121, 1.0
	v_div_fmas_f32 v117, v123, v131, v135
	s_mov_b64 vcc, s[8:9]
	v_pk_mul_f32 v[60:61], v[60:61], v[118:119] op_sel_hi:[1,0]
	v_pk_mul_f32 v[62:63], v[62:63], v[118:119] op_sel_hi:[1,0]
	v_pk_mul_f32 v[56:57], v[56:57], v[118:119] op_sel_hi:[1,0]
	v_pk_mul_f32 v[58:59], v[58:59], v[118:119] op_sel_hi:[1,0]
	v_pk_mul_f32 v[52:53], v[52:53], v[118:119] op_sel_hi:[1,0]
	v_pk_mul_f32 v[54:55], v[54:55], v[118:119] op_sel_hi:[1,0]
	v_pk_mul_f32 v[48:49], v[48:49], v[118:119] op_sel_hi:[1,0]
	v_pk_mul_f32 v[50:51], v[50:51], v[118:119] op_sel_hi:[1,0]
	v_div_fixup_f32 v118, v117, v119, 1.0
	v_pk_fma_f32 v[66:67], v[102:103], v[66:67], v[14:15]
	v_pk_fma_f32 v[64:65], v[104:105], v[64:65], v[12:13]
	v_div_fmas_f32 v117, v124, v132, v136
	v_cvt_pk_bf16_f32 v64, v64, v65
	v_cvt_pk_bf16_f32 v65, v66, v67
	v_div_fixup_f32 v66, v117, v120, 1.0
	v_pk_mul_f32 v[44:45], v[44:45], v[118:119] op_sel_hi:[1,0]
	v_pk_mul_f32 v[46:47], v[46:47], v[118:119] op_sel_hi:[1,0]
	v_pk_mul_f32 v[24:25], v[24:25], v[66:67] op_sel_hi:[1,0]
	v_pk_mul_f32 v[26:27], v[26:27], v[66:67] op_sel_hi:[1,0]
	v_pk_fma_f32 v[78:79], v[90:91], v[78:79], v[2:3]
	v_pk_fma_f32 v[76:77], v[92:93], v[76:77], v[0:1]
	v_pk_mul_f32 v[40:41], v[40:41], v[118:119] op_sel_hi:[1,0]
	v_pk_mul_f32 v[42:43], v[42:43], v[118:119] op_sel_hi:[1,0]
	v_pk_mul_f32 v[36:37], v[36:37], v[118:119] op_sel_hi:[1,0]
	v_pk_mul_f32 v[38:39], v[38:39], v[118:119] op_sel_hi:[1,0]
; __device__ __forceinline__ unsigned pk2(float lo, float hi) { f32x2 v = {lo, hi}; bf16x2_t b = __builtin_convertvector(v, bf16x2_t); return __builtin_bit_cast(unsigned, b); }
; __device__ __forceinline__ void norm_mod_phase(const Ctx& F, const float* xin, const float* gain, const float* shift, const float* scale) {
;     ...
;     for (int ch = gw; ch < T / 32; ch += NGW) {
;         const int row0 = ch * 32, b = row0 / S;
;         f32x4 ga[4], sh[4];
; #pragma unroll
;         for (int j = 0; j < 4; ++j) { const int c = 4 * ln + 256 * j; const f32x4 g = *(const f32x4*)(gain + c), sc = *(const f32x4*)(scale + (size_t)b * 6144 + c);
;             ga[j] = g * (sc + 1.0f); sh[j] = *(const f32x4*)(shift + (size_t)b * 6144 + c); }
;         for (int r = 0; r < 32; r += 4) {
;     ...
;                 for (int j = 0; j < 4; ++j) { const f32x4 o = v[u][j] * rstd * ga[j] + sh[j]; u32x2 w; w.x = pk2(o[0], o[1]); w.y = pk2(o[2], o[3]);
;                     *(u32x2*)(hb + (size_t)(row0 + r + u) * D + 4 * ln + 256 * j) = w; } }
	v_pk_mul_f32 v[32:33], v[32:33], v[118:119] op_sel_hi:[1,0]
	v_pk_mul_f32 v[34:35], v[34:35], v[118:119] op_sel_hi:[1,0]
	v_pk_fma_f32 v[62:63], v[90:91], v[62:63], v[2:3]
	v_pk_fma_f32 v[60:61], v[92:93], v[60:61], v[0:1]
	v_pk_mul_f32 v[20:21], v[20:21], v[66:67] op_sel_hi:[1,0]
	v_pk_mul_f32 v[22:23], v[22:23], v[66:67] op_sel_hi:[1,0]
	v_pk_mul_f32 v[16:17], v[16:17], v[66:67] op_sel_hi:[1,0]
	v_pk_mul_f32 v[18:19], v[18:19], v[66:67] op_sel_hi:[1,0]
	v_pk_mul_f32 v[28:29], v[28:29], v[66:67] op_sel_hi:[1,0]
	v_pk_mul_f32 v[30:31], v[30:31], v[66:67] op_sel_hi:[1,0]
	v_pk_fma_f32 v[46:47], v[90:91], v[46:47], v[2:3]
	v_pk_fma_f32 v[44:45], v[92:93], v[44:45], v[0:1]
	v_pk_fma_f32 v[26:27], v[90:91], v[26:27], v[2:3]
	v_pk_fma_f32 v[24:25], v[92:93], v[24:25], v[0:1]
	v_pk_fma_f32 v[70:71], v[94:95], v[70:71], v[6:7]
	v_pk_fma_f32 v[68:69], v[96:97], v[68:69], v[4:5]
	v_pk_fma_f32 v[74:75], v[98:99], v[74:75], v[10:11]
	v_pk_fma_f32 v[72:73], v[100:101], v[72:73], v[8:9]
	v_cvt_pk_bf16_f32 v76, v76, v77
	v_cvt_pk_bf16_f32 v77, v78, v79
	v_pk_fma_f32 v[58:59], v[94:95], v[58:59], v[6:7]
	v_pk_fma_f32 v[56:57], v[96:97], v[56:57], v[4:5]
	v_pk_fma_f32 v[54:55], v[98:99], v[54:55], v[10:11]
	v_pk_fma_f32 v[52:53], v[100:101], v[52:53], v[8:9]
	v_pk_fma_f32 v[50:51], v[102:103], v[50:51], v[14:15]
	v_pk_fma_f32 v[48:49], v[104:105], v[48:49], v[12:13]
	v_cvt_pk_bf16_f32 v60, v60, v61
	v_cvt_pk_bf16_f32 v61, v62, v63
	v_pk_fma_f32 v[42:43], v[94:95], v[42:43], v[6:7]
	v_pk_fma_f32 v[40:41], v[96:97], v[40:41], v[4:5]
	v_pk_fma_f32 v[38:39], v[98:99], v[38:39], v[10:11]
	v_pk_fma_f32 v[36:37], v[100:101], v[36:37], v[8:9]
	v_pk_fma_f32 v[34:35], v[102:103], v[34:35], v[14:15]
	v_pk_fma_f32 v[32:33], v[104:105], v[32:33], v[12:13]
	v_cvt_pk_bf16_f32 v44, v44, v45
	v_cvt_pk_bf16_f32 v45, v46, v47
	v_pk_fma_f32 v[22:23], v[94:95], v[22:23], v[6:7]
	v_pk_fma_f32 v[20:21], v[96:97], v[20:21], v[4:5]
	v_pk_fma_f32 v[18:19], v[98:99], v[18:19], v[10:11]
	v_pk_fma_f32 v[16:17], v[100:101], v[16:17], v[8:9]
	v_pk_fma_f32 v[30:31], v[102:103], v[30:31], v[14:15]
	v_pk_fma_f32 v[28:29], v[104:105], v[28:29], v[12:13]
	v_cvt_pk_bf16_f32 v24, v24, v25
	v_cvt_pk_bf16_f32 v25, v26, v27
	v_cvt_pk_bf16_f32 v68, v68, v69
	v_cvt_pk_bf16_f32 v69, v70, v71
	v_cvt_pk_bf16_f32 v70, v72, v73
	v_cvt_pk_bf16_f32 v71, v74, v75
	global_store_dwordx2 v[112:113], v[76:77], off
	global_store_dwordx2 v[112:113], v[68:69], off offset:512
	global_store_dwordx2 v[112:113], v[70:71], off offset:1024
	global_store_dwordx2 v[112:113], v[64:65], off offset:1536
	v_cvt_pk_bf16_f32 v56, v56, v57
	v_cvt_pk_bf16_f32 v57, v58, v59
	v_cvt_pk_bf16_f32 v52, v52, v53
	v_cvt_pk_bf16_f32 v53, v54, v55
	v_cvt_pk_bf16_f32 v48, v48, v49
	v_cvt_pk_bf16_f32 v49, v50, v51
	global_store_dwordx2 v[110:111], v[60:61], off
	global_store_dwordx2 v[110:111], v[56:57], off offset:512
	global_store_dwordx2 v[110:111], v[52:53], off offset:1024
	global_store_dwordx2 v[110:111], v[48:49], off offset:1536
	v_cvt_pk_bf16_f32 v40, v40, v41
	v_cvt_pk_bf16_f32 v41, v42, v43
	v_cvt_pk_bf16_f32 v36, v36, v37
	v_cvt_pk_bf16_f32 v37, v38, v39
	v_cvt_pk_bf16_f32 v32, v32, v33
	v_cvt_pk_bf16_f32 v33, v34, v35
	global_store_dwordx2 v[108:109], v[44:45], off
	global_store_dwordx2 v[108:109], v[40:41], off offset:512
	global_store_dwordx2 v[108:109], v[36:37], off offset:1024
	global_store_dwordx2 v[108:109], v[32:33], off offset:1536
	v_cvt_pk_bf16_f32 v20, v20, v21
	v_cvt_pk_bf16_f32 v21, v22, v23
	v_cvt_pk_bf16_f32 v16, v16, v17
	v_cvt_pk_bf16_f32 v17, v18, v19
	v_cvt_pk_bf16_f32 v18, v28, v29
	v_cvt_pk_bf16_f32 v19, v30, v31
	global_store_dwordx2 v[106:107], v[24:25], off
	global_store_dwordx2 v[106:107], v[20:21], off offset:512
	global_store_dwordx2 v[106:107], v[16:17], off offset:1024
	global_store_dwordx2 v[106:107], v[18:19], off offset:1536
	s_cbranch_scc0 .LBB0_164
	s_add_i32 s0, s0, s1
	s_add_i32 s20, s20, s3
	s_add_i32 s22, s22, s3
	s_add_i32 s24, s24, s3
	s_add_i32 s26, s26, s3
	s_cmpk_gt_i32 s0, 0x7ff
	s_cbranch_scc0 .LBB0_163

; __device__ __forceinline__ float wave_sum_fast(float x) { x = reduce16(x); return (rl_(x, 0) + rl_(x, 16)) + (rl_(x, 32) + rl_(x, 48)); }
; __device__ __forceinline__ void final_norm_phase(const Ctx& F) {
;     ...
;     for (int ch = gw; ch < T / 4; ch += NGW) {
;         u32x4 raw[4][2]; float s[4];
; #pragma unroll
;         for (int u = 0; u < 4; ++u)
; #pragma unroll
;             for (int j = 0; j < 2; ++j) raw[u][j] = *(const u32x4*)(xf + (size_t)(4 * ch + u) * D + 8 * ln + 512 * j);
; #pragma unroll
;         for (int u = 0; u < 4; ++u) { s[u] = 0.f;
; #pragma unroll
;             for (int j = 0; j < 2; ++j) { float f[8]; unpack8(raw[u][j], f);
; #pragma unroll
;                 for (int e = 0; e < 8; ++e) s[u] += f[e] * f[e]; }
;             s[u] = wave_sum_fast(s[u]); }
; #pragma unroll
;         for (int u = 0; u < 4; ++u) { const float rstd = 1.0f / sqrtf(s[u] * (1.0f / D) + 1e-6f); float* xr = F.out + (size_t)(4 * ch + u) * D;
; #pragma unroll
;             for (int j = 0; j < 2; ++j) { float f[8]; unpack8(raw[u][j], f);
;                 *(f32x4*)(xr + 8 * ln + 512 * j) = (f32x4){f[0] * rstd * ga[j][0], f[1] * rstd * ga[j][1], f[2] * rstd * ga[j][2], f[3] * rstd * ga[j][3]};
;                 *(f32x4*)(xr + 8 * ln + 512 * j + 4) = (f32x4){f[4] * rstd * ga[j][4], f[5] * rstd * ga[j][5], f[6] * rstd * ga[j][6], f[7] * rstd * ga[j][7]}; } }
.LBB0_1763:
	s_ashr_i32 s3, s2, 31
	s_lshl_b64 s[0:1], s[2:3], 11
	s_add_i32 s8, s2, 1
	v_lshl_add_u64 v[16:17], v[40:41], 0, s[0:1]
	s_ashr_i32 s9, s8, 31
	global_load_dwordx4 v[44:47], v[16:17], off offset:1024 nt
	global_load_dwordx4 v[48:51], v[16:17], off nt
	s_lshl_b64 s[0:1], s[8:9], 11
	s_add_i32 s6, s2, 2
	v_lshl_add_u64 v[52:53], v[40:41], 0, s[0:1]
	s_ashr_i32 s7, s6, 31
	s_add_i32 s4, s2, 3
	global_load_dwordx4 v[32:35], v[52:53], off offset:1024 nt
	s_lshl_b64 s[0:1], s[6:7], 11
	s_ashr_i32 s5, s4, 31
	v_lshl_add_u64 v[54:55], v[40:41], 0, s[0:1]
	s_lshl_b64 s[0:1], s[4:5], 11
	v_lshl_add_u64 v[56:57], v[40:41], 0, s[0:1]
	global_load_dwordx4 v[24:27], v[54:55], off offset:1024 nt
	global_load_dwordx4 v[16:19], v[56:57], off offset:1024 nt
	global_load_dwordx4 v[36:39], v[52:53], off nt
	global_load_dwordx4 v[28:31], v[54:55], off nt
	global_load_dwordx4 v[20:23], v[56:57], off nt
	s_lshl_b64 s[0:1], s[2:3], 12
	v_lshl_add_u64 v[72:73], v[42:43], 0, s[0:1]
	s_add_i32 s10, s10, s11
	s_add_i32 s2, s2, s12
	s_waitcnt vmcnt(0)
	v_lshlrev_b32_e32 v84, 16, v44
	v_lshlrev_b32_e32 v68, 16, v48
	v_and_b32_e32 v69, 0xffff0000, v48
	v_lshlrev_b32_e32 v70, 16, v49
	v_and_b32_e32 v71, 0xffff0000, v49
	v_pk_mul_f32 v[86:87], v[68:69], v[68:69]
	v_pk_mul_f32 v[88:89], v[70:71], v[70:71]
	v_and_b32_e32 v62, 0xffff0000, v34
	v_lshlrev_b32_e32 v63, 16, v34
	v_and_b32_e32 v56, 0xffff0000, v35
	v_lshlrev_b32_e32 v57, 16, v35
	v_and_b32_e32 v34, 0xffff0000, v17
	v_lshlrev_b32_e32 v35, 16, v17
	v_add_f32_e32 v17, v86, v87
	v_lshlrev_b32_e32 v80, 16, v50
	v_and_b32_e32 v81, 0xffff0000, v50
	v_add_f32_e32 v17, v88, v17
	v_pk_mul_f32 v[90:91], v[80:81], v[80:81]
	v_add_f32_e32 v17, v89, v17
	v_lshlrev_b32_e32 v82, 16, v51
	v_and_b32_e32 v83, 0xffff0000, v51
	v_add_f32_e32 v17, v90, v17
	v_pk_mul_f32 v[92:93], v[82:83], v[82:83]
	v_add_f32_e32 v17, v91, v17
	v_and_b32_e32 v85, 0xffff0000, v44
	v_add_f32_e32 v17, v92, v17
	v_pk_mul_f32 v[94:95], v[84:85], v[84:85]
	v_add_f32_e32 v17, v93, v17
	v_and_b32_e32 v74, 0xffff0000, v45
	v_lshlrev_b32_e32 v75, 16, v45
	v_add_f32_e32 v17, v94, v17
	v_pk_mul_f32 v[50:51], v[74:75], v[74:75]
	v_add_f32_e32 v17, v95, v17
	v_and_b32_e32 v76, 0xffff0000, v46
	v_lshlrev_b32_e32 v77, 16, v46
	v_add_f32_e32 v17, v51, v17
	v_pk_mul_f32 v[52:53], v[76:77], v[76:77]
	v_add_f32_e32 v17, v50, v17
	v_and_b32_e32 v78, 0xffff0000, v47
	v_lshlrev_b32_e32 v79, 16, v47
	v_add_f32_e32 v17, v53, v17
	v_pk_mul_f32 v[54:55], v[78:79], v[78:79]
	v_add_f32_e32 v17, v52, v17
	v_add_f32_e32 v17, v55, v17
	v_add_f32_e32 v17, v54, v17
	v_and_b32_e32 v48, 0xffff0000, v25
	v_lshlrev_b32_e32 v49, 16, v25
	v_add_f32_dpp v17, v17, v17 quad_perm:[1,0,3,2] row_mask:0xf bank_mask:0xf bound_ctrl:1
	v_and_b32_e32 v64, 0xffff0000, v33
	v_lshlrev_b32_e32 v65, 16, v33
	v_add_f32_dpp v17, v17, v17 quad_perm:[2,3,0,1] row_mask:0xf bank_mask:0xf bound_ctrl:1
	v_and_b32_e32 v91, 0xffff0000, v32
	v_pk_mul_f32 v[96:97], v[64:65], v[64:65]
	v_add_f32_dpp v17, v17, v17 row_half_mirror row_mask:0xf bank_mask:0xf bound_ctrl:1
	v_pk_mul_f32 v[98:99], v[62:63], v[62:63]
	v_pk_mul_f32 v[100:101], v[56:57], v[56:57]
	v_add_f32_dpp v17, v17, v17 row_mirror row_mask:0xf bank_mask:0xf bound_ctrl:1
	v_pk_mul_f32 v[60:61], v[48:49], v[48:49]
	v_readlane_b32 s3, v17, 16
	v_readlane_b32 s14, v17, 48
	v_readlane_b32 s0, v17, 0
	v_readlane_b32 s1, v17, 32
	v_mov_b32_e32 v50, s3
	v_mov_b32_e32 v51, s14
	v_pk_add_f32 v[50:51], s[0:1], v[50:51]
	v_and_b32_e32 v46, 0xffff0000, v26
	v_add_f32_e32 v17, v50, v51
	v_fmamk_f32 v17, v17, 0x3a800000, v66
	v_mul_f32_e32 v25, 0x4f800000, v17
	v_cmp_gt_f32_e32 vcc, s13, v17
	v_lshlrev_b32_e32 v47, 16, v26
	v_pk_mul_f32 v[58:59], v[46:47], v[46:47]
	v_cndmask_b32_e32 v17, v17, v25, vcc
	v_sqrt_f32_e32 v25, v17
	v_and_b32_e32 v44, 0xffff0000, v27
	v_lshlrev_b32_e32 v45, 16, v27
	v_pk_mul_f32 v[86:87], v[44:45], v[44:45]
	v_add_u32_e32 v33, -1, v25
	v_add_u32_e32 v54, 1, v25
	v_fma_f32 v55, -v33, v25, v17
	v_fma_f32 v88, -v54, v25, v17
	v_cmp_ge_f32_e64 s[0:1], 0, v55
	v_pk_mul_f32 v[52:53], v[34:35], v[34:35]
	v_and_b32_e32 v26, 0xffff0000, v18
	v_cndmask_b32_e64 v25, v25, v33, s[0:1]
	v_cmp_lt_f32_e64 s[0:1], 0, v88
	v_lshlrev_b32_e32 v27, 16, v18
	v_pk_mul_f32 v[50:51], v[26:27], v[26:27]
	v_cndmask_b32_e64 v25, v25, v54, s[0:1]
	v_mul_f32_e32 v33, 0x37800000, v25
	v_cndmask_b32_e32 v25, v25, v33, vcc
	v_cmp_class_f32_e32 vcc, v17, v67
	v_and_b32_e32 v18, 0xffff0000, v19
	v_lshlrev_b32_e32 v19, 16, v19
	v_cndmask_b32_e32 v17, v25, v17, vcc
	v_div_scale_f32 v25, s[0:1], v17, v17, 1.0
	v_rcp_f32_e32 v33, v25
	v_div_scale_f32 v88, vcc, 1.0, v17, 1.0
	v_pk_mul_f32 v[54:55], v[18:19], v[18:19]
	v_fma_f32 v89, -v25, v33, 1.0
	v_fmac_f32_e32 v33, v89, v33
	v_mul_f32_e32 v89, v88, v33
	v_fma_f32 v90, -v25, v89, v88
	v_fmac_f32_e32 v89, v90, v33
	v_fma_f32 v25, -v25, v89, v88
	v_div_fmas_f32 v25, v25, v33, v89
	v_div_fixup_f32 v88, v25, v17, 1.0
	v_pk_mul_f32 v[68:69], v[88:89], v[68:69] op_sel_hi:[0,1]
	v_pk_mul_f32 v[70:71], v[88:89], v[70:71] op_sel_hi:[0,1]
	s_waitcnt lgkmcnt(0)
; __device__ __forceinline__ float wave_sum_fast(float x) { x = reduce16(x); return (rl_(x, 0) + rl_(x, 16)) + (rl_(x, 32) + rl_(x, 48)); }
; __device__ __forceinline__ void final_norm_phase(const Ctx& F) {
;     ...
;         for (int u = 0; u < 4; ++u) { s[u] = 0.f;
; #pragma unroll
;             for (int j = 0; j < 2; ++j) { float f[8]; unpack8(raw[u][j], f);
; #pragma unroll
;                 for (int e = 0; e < 8; ++e) s[u] += f[e] * f[e]; }
;             s[u] = wave_sum_fast(s[u]); }
; #pragma unroll
;         for (int u = 0; u < 4; ++u) { const float rstd = 1.0f / sqrtf(s[u] * (1.0f / D) + 1e-6f); float* xr = F.out + (size_t)(4 * ch + u) * D;
; #pragma unroll
;             for (int j = 0; j < 2; ++j) { float f[8]; unpack8(raw[u][j], f);
;                 *(f32x4*)(xr + 8 * ln + 512 * j) = (f32x4){f[0] * rstd * ga[j][0], f[1] * rstd * ga[j][1], f[2] * rstd * ga[j][2], f[3] * rstd * ga[j][3]};
;                 *(f32x4*)(xr + 8 * ln + 512 * j + 4) = (f32x4){f[4] * rstd * ga[j][4], f[5] * rstd * ga[j][5], f[6] * rstd * ga[j][6], f[7] * rstd * ga[j][7]}; } }
	v_pk_mul_f32 v[70:71], v[2:3], v[70:71]
	v_pk_mul_f32 v[68:69], v[0:1], v[68:69]
	global_store_dwordx4 v[72:73], v[68:71], off
	v_lshlrev_b32_e32 v90, 16, v32
	v_pk_mul_f32 v[32:33], v[90:91], v[90:91]
	v_pk_mul_f32 v[68:69], v[88:89], v[80:81] op_sel_hi:[0,1]
	v_pk_mul_f32 v[70:71], v[88:89], v[82:83] op_sel_hi:[0,1]
	v_pk_mul_f32 v[70:71], v[6:7], v[70:71]
	v_pk_mul_f32 v[68:69], v[4:5], v[68:69]
	global_store_dwordx4 v[72:73], v[68:71], off offset:16
	v_lshlrev_b32_e32 v80, 16, v38
	v_and_b32_e32 v81, 0xffff0000, v38
	v_pk_mul_f32 v[68:69], v[88:89], v[84:85] op_sel_hi:[0,1]
	v_pk_mul_f32 v[70:71], v[88:89], v[74:75] op_sel_hi:[0,1]
	v_pk_mul_f32 v[70:71], v[10:11], v[70:71] op_sel:[0,1] op_sel_hi:[1,0]
	v_pk_mul_f32 v[68:69], v[8:9], v[68:69]
	global_store_dwordx4 v[72:73], v[68:71], off offset:2048
	v_pk_mul_f32 v[82:83], v[80:81], v[80:81]
	v_lshlrev_b32_e32 v84, 16, v39
	v_lshlrev_b32_e32 v70, 16, v36
	v_and_b32_e32 v71, 0xffff0000, v36
	v_pk_mul_f32 v[68:69], v[88:89], v[76:77] op_sel_hi:[0,1]
	v_pk_mul_f32 v[74:75], v[70:71], v[70:71]
	v_lshlrev_b32_e32 v76, 16, v37
	v_and_b32_e32 v77, 0xffff0000, v37
	v_pk_mul_f32 v[36:37], v[76:77], v[76:77]
	v_add_f32_e32 v17, v74, v75
	v_add_f32_e32 v17, v36, v17
	v_add_f32_e32 v17, v37, v17
	v_and_b32_e32 v85, 0xffff0000, v39
	v_add_f32_e32 v17, v82, v17
	v_pk_mul_f32 v[38:39], v[84:85], v[84:85]
	v_add_f32_e32 v17, v83, v17
	v_add_f32_e32 v17, v38, v17
	v_add_f32_e32 v17, v39, v17
	v_add_f32_e32 v17, v32, v17
	v_add_f32_e32 v17, v33, v17
	v_add_f32_e32 v17, v97, v17
	v_add_f32_e32 v17, v96, v17
	v_add_f32_e32 v17, v99, v17
	v_add_f32_e32 v17, v98, v17
	v_add_f32_e32 v17, v101, v17
	v_add_f32_e32 v17, v100, v17
	v_pk_mul_f32 v[36:37], v[12:13], v[68:69] op_sel:[0,1] op_sel_hi:[1,0]
	v_lshlrev_b32_e32 v74, 16, v31
	v_add_f32_dpp v17, v17, v17 quad_perm:[1,0,3,2] row_mask:0xf bank_mask:0xf bound_ctrl:1
	v_and_b32_e32 v75, 0xffff0000, v31
	s_nop 0
	v_add_f32_dpp v17, v17, v17 quad_perm:[2,3,0,1] row_mask:0xf bank_mask:0xf bound_ctrl:1
	s_nop 1
	v_add_f32_dpp v17, v17, v17 row_half_mirror row_mask:0xf bank_mask:0xf bound_ctrl:1
	s_nop 1
	v_add_f32_dpp v17, v17, v17 row_mirror row_mask:0xf bank_mask:0xf bound_ctrl:1
	s_nop 0
	v_readlane_b32 s3, v17, 16
	v_readlane_b32 s14, v17, 48
	v_readlane_b32 s0, v17, 0
	v_readlane_b32 s1, v17, 32
	v_mov_b32_e32 v32, s3
	v_mov_b32_e32 v33, s14
	v_pk_add_f32 v[32:33], s[0:1], v[32:33]
	s_nop 0
	v_add_f32_e32 v17, v32, v33
	v_fmamk_f32 v17, v17, 0x3a800000, v66
	v_mul_f32_e32 v25, 0x4f800000, v17
	v_cmp_gt_f32_e32 vcc, s13, v17
	v_pk_mul_f32 v[32:33], v[88:89], v[78:79] op_sel_hi:[0,1]
	v_pk_mul_f32 v[38:39], v[14:15], v[32:33] op_sel:[0,1] op_sel_hi:[1,0]
	v_cndmask_b32_e32 v17, v17, v25, vcc
	v_sqrt_f32_e32 v25, v17
	global_store_dwordx4 v[72:73], v[36:39], off offset:2064
	v_add_u32_e32 v32, -1, v25
	v_fma_f32 v33, -v32, v25, v17
	v_cmp_ge_f32_e64 s[0:1], 0, v33
	v_add_u32_e32 v33, 1, v25
	s_nop 0
	v_cndmask_b32_e64 v32, v25, v32, s[0:1]
	v_fma_f32 v25, -v33, v25, v17
	v_cmp_lt_f32_e64 s[0:1], 0, v25
	s_nop 1
	v_cndmask_b32_e64 v25, v32, v33, s[0:1]
	v_mul_f32_e32 v32, 0x37800000, v25
	v_cndmask_b32_e32 v25, v25, v32, vcc
	v_cmp_class_f32_e32 vcc, v17, v67
	s_nop 1
	v_cndmask_b32_e32 v17, v25, v17, vcc
	v_div_scale_f32 v25, s[0:1], v17, v17, 1.0
	v_rcp_f32_e32 v68, v25
	s_lshl_b64 s[0:1], s[8:9], 12
	v_lshl_add_u64 v[32:33], v[42:43], 0, s[0:1]
	v_fma_f32 v36, -v25, v68, 1.0
	v_fmac_f32_e32 v68, v36, v68
	v_div_scale_f32 v36, vcc, 1.0, v17, 1.0
	v_mul_f32_e32 v37, v36, v68
	v_fma_f32 v38, -v25, v37, v36
	v_fmac_f32_e32 v37, v38, v68
	v_fma_f32 v25, -v25, v37, v36
	v_div_fmas_f32 v25, v25, v68, v37
	v_div_fixup_f32 v68, v25, v17, 1.0
	v_pk_mul_f32 v[36:37], v[68:69], v[70:71] op_sel_hi:[0,1]
	v_pk_mul_f32 v[38:39], v[68:69], v[76:77] op_sel_hi:[0,1]
	v_pk_mul_f32 v[38:39], v[2:3], v[38:39]
	v_pk_mul_f32 v[36:37], v[0:1], v[36:37]
	global_store_dwordx4 v[32:33], v[36:39], off
	v_lshlrev_b32_e32 v70, 16, v30
	v_and_b32_e32 v71, 0xffff0000, v30
	v_pk_mul_f32 v[36:37], v[68:69], v[80:81] op_sel_hi:[0,1]
	v_pk_mul_f32 v[38:39], v[68:69], v[84:85] op_sel_hi:[0,1]
	v_pk_mul_f32 v[38:39], v[6:7], v[38:39]
	v_pk_mul_f32 v[36:37], v[4:5], v[36:37]
	global_store_dwordx4 v[32:33], v[36:39], off offset:16
	v_pk_mul_f32 v[72:73], v[70:71], v[70:71]
	v_pk_mul_f32 v[30:31], v[74:75], v[74:75]
	v_pk_mul_f32 v[36:37], v[68:69], v[90:91] op_sel_hi:[0,1]
	v_pk_mul_f32 v[38:39], v[68:69], v[64:65] op_sel_hi:[0,1]
	v_pk_mul_f32 v[38:39], v[10:11], v[38:39] op_sel:[0,1] op_sel_hi:[1,0]
	v_pk_mul_f32 v[36:37], v[8:9], v[36:37]
	global_store_dwordx4 v[32:33], v[36:39], off offset:2048
	v_lshlrev_b32_e32 v64, 16, v29
	v_and_b32_e32 v65, 0xffff0000, v29
	v_lshlrev_b32_e32 v38, 16, v28
	v_and_b32_e32 v39, 0xffff0000, v28
	v_pk_mul_f32 v[36:37], v[68:69], v[62:63] op_sel_hi:[0,1]
	v_pk_mul_f32 v[62:63], v[38:39], v[38:39]
	v_pk_mul_f32 v[28:29], v[64:65], v[64:65]
	v_add_f32_e32 v17, v62, v63
	v_add_f32_e32 v17, v28, v17
	v_add_f32_e32 v17, v29, v17
	v_add_f32_e32 v17, v72, v17
	v_add_f32_e32 v17, v73, v17
	v_lshlrev_b32_e32 v76, 16, v24
	v_and_b32_e32 v77, 0xffff0000, v24
	v_add_f32_e32 v17, v30, v17
	v_pk_mul_f32 v[24:25], v[76:77], v[76:77]
	v_add_f32_e32 v17, v31, v17
	v_add_f32_e32 v17, v24, v17
	v_add_f32_e32 v17, v25, v17
	v_add_f32_e32 v17, v61, v17
	v_add_f32_e32 v17, v60, v17
	v_add_f32_e32 v17, v59, v17
	v_add_f32_e32 v17, v58, v17
	v_add_f32_e32 v17, v87, v17
	v_add_f32_e32 v17, v86, v17
	v_pk_mul_f32 v[28:29], v[12:13], v[36:37] op_sel:[0,1] op_sel_hi:[1,0]
	v_and_b32_e32 v59, 0xffff0000, v16
	v_add_f32_dpp v17, v17, v17 quad_perm:[1,0,3,2] row_mask:0xf bank_mask:0xf bound_ctrl:1
; __device__ __forceinline__ float wave_sum_fast(float x) { x = reduce16(x); return (rl_(x, 0) + rl_(x, 16)) + (rl_(x, 32) + rl_(x, 48)); }
; __device__ __forceinline__ void final_norm_phase(const Ctx& F) {
;     ...
;         for (int u = 0; u < 4; ++u) { s[u] = 0.f;
; #pragma unroll
;             for (int j = 0; j < 2; ++j) { float f[8]; unpack8(raw[u][j], f);
; #pragma unroll
;                 for (int e = 0; e < 8; ++e) s[u] += f[e] * f[e]; }
;             s[u] = wave_sum_fast(s[u]); }
; #pragma unroll
;         for (int u = 0; u < 4; ++u) { const float rstd = 1.0f / sqrtf(s[u] * (1.0f / D) + 1e-6f); float* xr = F.out + (size_t)(4 * ch + u) * D;
; #pragma unroll
;             for (int j = 0; j < 2; ++j) { float f[8]; unpack8(raw[u][j], f);
;                 *(f32x4*)(xr + 8 * ln + 512 * j) = (f32x4){f[0] * rstd * ga[j][0], f[1] * rstd * ga[j][1], f[2] * rstd * ga[j][2], f[3] * rstd * ga[j][3]};
;                 *(f32x4*)(xr + 8 * ln + 512 * j + 4) = (f32x4){f[4] * rstd * ga[j][4], f[5] * rstd * ga[j][5], f[6] * rstd * ga[j][6], f[7] * rstd * ga[j][7]}; } }
;     }
	s_nop 1
	v_add_f32_dpp v17, v17, v17 quad_perm:[2,3,0,1] row_mask:0xf bank_mask:0xf bound_ctrl:1
	s_nop 1
	v_add_f32_dpp v17, v17, v17 row_half_mirror row_mask:0xf bank_mask:0xf bound_ctrl:1
	s_nop 1
	v_add_f32_dpp v17, v17, v17 row_mirror row_mask:0xf bank_mask:0xf bound_ctrl:1
	s_nop 0
	v_readlane_b32 s3, v17, 16
	v_readlane_b32 s8, v17, 48
	v_readlane_b32 s0, v17, 0
	v_readlane_b32 s1, v17, 32
	v_mov_b32_e32 v24, s3
	v_mov_b32_e32 v25, s8
	v_pk_add_f32 v[24:25], s[0:1], v[24:25]
	s_nop 0
	v_add_f32_e32 v17, v24, v25
	v_fmamk_f32 v17, v17, 0x3a800000, v66
	v_mul_f32_e32 v24, 0x4f800000, v17
	v_cmp_gt_f32_e32 vcc, s13, v17
	s_nop 1
	v_cndmask_b32_e32 v17, v17, v24, vcc
	v_sqrt_f32_e32 v58, v17
	v_pk_mul_f32 v[24:25], v[68:69], v[56:57] op_sel_hi:[0,1]
	v_pk_mul_f32 v[30:31], v[14:15], v[24:25] op_sel:[0,1] op_sel_hi:[1,0]
	global_store_dwordx4 v[32:33], v[28:31], off offset:2064
	v_add_u32_e32 v24, -1, v58
	v_fma_f32 v25, -v24, v58, v17
	v_cmp_ge_f32_e64 s[0:1], 0, v25
	v_add_u32_e32 v25, 1, v58
	v_fma_f32 v36, -v25, v58, v17
	v_cndmask_b32_e64 v24, v58, v24, s[0:1]
	v_cmp_lt_f32_e64 s[0:1], 0, v36
	v_lshlrev_b32_e32 v56, 16, v23
	v_and_b32_e32 v57, 0xffff0000, v23
	v_cndmask_b32_e64 v24, v24, v25, s[0:1]
	v_mul_f32_e32 v25, 0x37800000, v24
	v_cndmask_b32_e32 v24, v24, v25, vcc
	v_cmp_class_f32_e32 vcc, v17, v67
	v_lshlrev_b32_e32 v58, 16, v16
	s_nop 0
	v_cndmask_b32_e32 v17, v24, v17, vcc
	v_div_scale_f32 v36, s[0:1], v17, v17, 1.0
	v_rcp_f32_e32 v37, v36
	s_lshl_b64 s[0:1], s[6:7], 12
	v_lshl_add_u64 v[24:25], v[42:43], 0, s[0:1]
	v_fma_f32 v28, -v36, v37, 1.0
	v_fmac_f32_e32 v37, v28, v37
	v_div_scale_f32 v28, vcc, 1.0, v17, 1.0
	v_mul_f32_e32 v29, v28, v37
	v_fma_f32 v30, -v36, v29, v28
	v_fmac_f32_e32 v29, v30, v37
	v_fma_f32 v28, -v36, v29, v28
	v_div_fmas_f32 v28, v28, v37, v29
	v_div_fixup_f32 v32, v28, v17, 1.0
	v_pk_mul_f32 v[28:29], v[32:33], v[38:39] op_sel_hi:[0,1]
	v_pk_mul_f32 v[30:31], v[32:33], v[64:65] op_sel_hi:[0,1]
	v_pk_mul_f32 v[30:31], v[2:3], v[30:31]
	v_pk_mul_f32 v[28:29], v[0:1], v[28:29]
	global_store_dwordx4 v[24:25], v[28:31], off
	v_lshlrev_b32_e32 v38, 16, v21
	v_and_b32_e32 v39, 0xffff0000, v21
	v_pk_mul_f32 v[28:29], v[32:33], v[70:71] op_sel_hi:[0,1]
	v_pk_mul_f32 v[30:31], v[32:33], v[74:75] op_sel_hi:[0,1]
	v_pk_mul_f32 v[30:31], v[6:7], v[30:31]
	v_pk_mul_f32 v[28:29], v[4:5], v[28:29]
	global_store_dwordx4 v[24:25], v[28:31], off offset:16
	v_pk_mul_f32 v[16:17], v[58:59], v[58:59]
	s_nop 0
	v_pk_mul_f32 v[28:29], v[32:33], v[76:77] op_sel_hi:[0,1]
	v_pk_mul_f32 v[30:31], v[32:33], v[48:49] op_sel_hi:[0,1]
	v_pk_mul_f32 v[30:31], v[10:11], v[30:31] op_sel:[0,1] op_sel_hi:[1,0]
	v_pk_mul_f32 v[28:29], v[8:9], v[28:29]
	global_store_dwordx4 v[24:25], v[28:31], off offset:2048
	s_nop 1
	v_lshlrev_b32_e32 v30, 16, v20
	v_and_b32_e32 v31, 0xffff0000, v20
	v_pk_mul_f32 v[36:37], v[30:31], v[30:31]
	v_pk_mul_f32 v[28:29], v[32:33], v[46:47] op_sel_hi:[0,1]
	v_pk_mul_f32 v[20:21], v[38:39], v[38:39]
	v_add_f32_e32 v33, v36, v37
	v_lshlrev_b32_e32 v46, 16, v22
	v_and_b32_e32 v47, 0xffff0000, v22
	v_add_f32_e32 v20, v20, v33
	v_pk_mul_f32 v[48:49], v[46:47], v[46:47]
	v_add_f32_e32 v20, v21, v20
	v_add_f32_e32 v20, v48, v20
	v_pk_mul_f32 v[22:23], v[56:57], v[56:57]
	v_add_f32_e32 v20, v49, v20
	v_add_f32_e32 v20, v22, v20
	v_add_f32_e32 v20, v23, v20
	v_add_f32_e32 v16, v16, v20
	v_add_f32_e32 v16, v17, v16
	v_add_f32_e32 v16, v53, v16
	v_add_f32_e32 v16, v52, v16
	v_add_f32_e32 v16, v51, v16
	v_add_f32_e32 v16, v50, v16
	v_add_f32_e32 v16, v55, v16
	v_add_f32_e32 v16, v54, v16
	v_pk_mul_f32 v[20:21], v[12:13], v[28:29] op_sel:[0,1] op_sel_hi:[1,0]
	s_nop 0
	v_add_f32_dpp v16, v16, v16 quad_perm:[1,0,3,2] row_mask:0xf bank_mask:0xf bound_ctrl:1
	s_nop 1
	v_add_f32_dpp v16, v16, v16 quad_perm:[2,3,0,1] row_mask:0xf bank_mask:0xf bound_ctrl:1
	s_nop 1
	v_add_f32_dpp v16, v16, v16 row_half_mirror row_mask:0xf bank_mask:0xf bound_ctrl:1
	s_nop 1
	v_add_f32_dpp v16, v16, v16 row_mirror row_mask:0xf bank_mask:0xf bound_ctrl:1
	s_nop 0
	v_readlane_b32 s3, v16, 16
	v_readlane_b32 s6, v16, 48
	v_readlane_b32 s0, v16, 0
	v_readlane_b32 s1, v16, 32
	v_mov_b32_e32 v16, s3
	v_mov_b32_e32 v17, s6
	v_pk_add_f32 v[16:17], s[0:1], v[16:17]
	s_nop 0
	v_add_f32_e32 v16, v16, v17
	v_fmamk_f32 v16, v16, 0x3a800000, v66
	v_mul_f32_e32 v17, 0x4f800000, v16
	v_cmp_gt_f32_e32 vcc, s13, v16
	s_nop 1
	v_cndmask_b32_e32 v33, v16, v17, vcc
	v_sqrt_f32_e32 v36, v33
	v_pk_mul_f32 v[16:17], v[32:33], v[44:45] op_sel_hi:[0,1]
	v_pk_mul_f32 v[22:23], v[14:15], v[16:17] op_sel:[0,1] op_sel_hi:[1,0]
	global_store_dwordx4 v[24:25], v[20:23], off offset:2064
	v_add_u32_e32 v16, -1, v36
	v_fma_f32 v17, -v16, v36, v33
	v_cmp_ge_f32_e64 s[0:1], 0, v17
	v_add_u32_e32 v17, 1, v36
	v_fma_f32 v28, -v17, v36, v33
	v_cndmask_b32_e64 v16, v36, v16, s[0:1]
	v_cmp_lt_f32_e64 s[0:1], 0, v28
	s_nop 1
	v_cndmask_b32_e64 v16, v16, v17, s[0:1]
	v_mul_f32_e32 v17, 0x37800000, v16
	v_cndmask_b32_e32 v16, v16, v17, vcc
	v_cmp_class_f32_e32 vcc, v33, v67
	s_nop 1
	v_cndmask_b32_e32 v16, v16, v33, vcc
	v_div_scale_f32 v17, s[0:1], v16, v16, 1.0
	v_rcp_f32_e32 v28, v17
	s_lshl_b64 s[0:1], s[4:5], 12
	v_lshl_add_u64 v[24:25], v[42:43], 0, s[0:1]
	s_cmpk_lt_i32 s10, 0x4000
	v_fma_f32 v20, -v17, v28, 1.0
	v_fmac_f32_e32 v28, v20, v28
	v_div_scale_f32 v20, vcc, 1.0, v16, 1.0
	v_mul_f32_e32 v21, v20, v28
	v_fma_f32 v22, -v17, v21, v20
	v_fmac_f32_e32 v21, v22, v28
	v_fma_f32 v17, -v17, v21, v20
	v_div_fmas_f32 v17, v17, v28, v21
	v_div_fixup_f32 v16, v17, v16, 1.0
	v_pk_mul_f32 v[20:21], v[16:17], v[30:31] op_sel_hi:[0,1]
	v_pk_mul_f32 v[22:23], v[16:17], v[38:39] op_sel_hi:[0,1]
	v_pk_mul_f32 v[22:23], v[2:3], v[22:23]
	v_pk_mul_f32 v[20:21], v[0:1], v[20:21]
	global_store_dwordx4 v[24:25], v[20:23], off
	s_nop 1
	v_pk_mul_f32 v[20:21], v[16:17], v[46:47] op_sel_hi:[0,1]
	v_pk_mul_f32 v[22:23], v[16:17], v[56:57] op_sel_hi:[0,1]
	v_pk_mul_f32 v[22:23], v[6:7], v[22:23]
	v_pk_mul_f32 v[20:21], v[4:5], v[20:21]
	global_store_dwordx4 v[24:25], v[20:23], off offset:16
	s_nop 1
	v_pk_mul_f32 v[20:21], v[16:17], v[58:59] op_sel_hi:[0,1]
	v_pk_mul_f32 v[22:23], v[16:17], v[34:35] op_sel_hi:[0,1]
	v_pk_mul_f32 v[22:23], v[10:11], v[22:23] op_sel:[0,1] op_sel_hi:[1,0]
	v_pk_mul_f32 v[20:21], v[8:9], v[20:21]
	global_store_dwordx4 v[24:25], v[20:23], off offset:2048
	s_nop 1
	v_pk_mul_f32 v[20:21], v[16:17], v[26:27] op_sel_hi:[0,1]
	v_pk_mul_f32 v[16:17], v[16:17], v[18:19] op_sel_hi:[0,1]
	v_pk_mul_f32 v[18:19], v[14:15], v[16:17] op_sel:[0,1] op_sel_hi:[1,0]
	v_pk_mul_f32 v[16:17], v[12:13], v[20:21] op_sel:[0,1] op_sel_hi:[1,0]
	global_store_dwordx4 v[24:25], v[16:19], off offset:2064
	s_cbranch_scc1 .LBB0_1763
